# k17 plus: one static s_setprio 1 for waves 4-7 across the MLA attention loop
# speedup vs baseline: 1.0018x; 1.0018x over previous
; __device__ __forceinline__ unsigned cvt_pk_bf16(float lo, float hi) { unsigned r; asm volatile("v_cvt_pk_bf16_f32 %0, %1, %2" : "=v"(r) : "v"(lo), "v"(hi)); return r; }
; __device__ __forceinline__ float xhalf_sum(float v) { auto rr = __builtin_amdgcn_permlane32_swap(__float_as_uint(v), __float_as_uint(v), false, false); return __uint_as_float(rr[0]) + __uint_as_float(rr[1]); }
; __device__ __forceinline__ void attn_mla_phase(LAS unsigned char* lds, const bf16_t* QB, const bf16_t* KV, const bf16_t* KRR, bf16_t* O, int G, int bx) {
;     ...
;     const int skey = tid >> 3, sch = tid & 7, rkey = tid >> 2, rch = tid & 3;
;     const int kdst = skey * 208 + sch * 16, rdst = rkey * 208 + 128 + rch * 16, vdst = (sch >> 2) * 4096 + skey * 64 + (sch & 3) * 16;
;     const unsigned trb = (unsigned)(size_t)(lds + VOFF) + (unsigned)((4 * hi + ((lane & 15) >> 2)) * 64 + 32 * ((lane >> 4) & 1) + 8 * (lane & 3));
;     ...
;         l = xhalf_sum(l);
;         const float inv = 1.f / l;
;         bf16_t* orow = O + qrow * DM + h * 64 + 4 * hi;
; #pragma unroll
;         for (int g4 = 0; g4 < 4; ++g4) {
;             u32x2 w0, w1;
;             w0.x = cvt_pk_bf16(o0[4 * g4] * inv, o0[4 * g4 + 1] * inv); w0.y = cvt_pk_bf16(o0[4 * g4 + 2] * inv, o0[4 * g4 + 3] * inv);
;             w1.x = cvt_pk_bf16(o1[4 * g4] * inv, o1[4 * g4 + 1] * inv); w1.y = cvt_pk_bf16(o1[4 * g4 + 2] * inv, o1[4 * g4 + 3] * inv);
;             *(u32x2*)(orow + 8 * g4) = w0; *(u32x2*)(orow + 32 + 8 * g4) = w1;
;         }
.LBB0_763:
	s_or_b64 exec, exec, s[20:21]
	s_add_u32 s36, s18, 0xde00000
	v_lshlrev_b32_e32 v0, 2, v20
	v_lshrrev_b32_e32 v3, 2, v14
	s_addc_u32 s37, s19, 0
	s_ashr_i32 s2, s1, 3
	v_and_or_b32 v3, v3, 3, v0
	v_lshlrev_b32_e32 v5, 1, v14
	v_lshlrev_b32_e32 v6, 3, v14
	s_and_b64 s[8:9], s[12:13], exec
	v_lshlrev_b32_e32 v3, 6, v3
	v_and_b32_e32 v5, 32, v5
	v_and_b32_e32 v6, 24, v6
	s_cselect_b32 s20, s2, s1
	v_or3_b32 v5, v3, v5, v6
	v_readlane_b32 s1, v254, 63
	v_lshlrev_b32_e32 v2, 3, v22
	v_lshlrev_b32_e32 v2, 1, v2
	v_add_u32_e32 v201, s1, v5
	v_readlane_b32 s1, v255, 0
	v_mov_b32_e32 v3, v19
	v_lshlrev_b32_e32 v1, 3, v20
	v_add_u32_e32 v202, s1, v5
	v_readlane_b32 s1, v255, 1
	v_lshlrev_b32_e32 v4, 3, v21
	v_lshl_add_u64 v[164:165], s[16:17], 0, v[2:3]
	v_add_u32_e32 v203, s1, v5
	v_readlane_b32 s1, v255, 2
	v_mad_u32_u24 v2, v15, s10, 0
	v_add_u32_e32 v3, v9, v18
	v_add_u32_e32 v204, s1, v5
	v_readlane_b32 s1, v255, 3
	v_mov_b32_e32 v104, v19
	v_mov_b32_e32 v105, v19
	v_add_u32_e32 v205, s1, v5
	v_readlane_b32 s1, v255, 4
	v_mov_b32_e32 v106, v19
	v_mov_b32_e32 v107, v19
	v_add_u32_e32 v206, s1, v5
	v_readlane_b32 s1, v255, 5
	v_lshlrev_b32_e32 v18, 1, v4
	v_lshlrev_b32_e32 v166, 1, v1
	v_add_u32_e32 v207, s1, v5
	v_readlane_b32 s1, v255, 6
	v_lshlrev_b32_e32 v168, 1, v0
	v_add_u32_e32 v234, v2, v8
	v_add_u32_e32 v208, s1, v5
	v_readlane_b32 s1, v255, 7
	v_add_u32_e32 v235, 0, v3
	s_waitcnt lgkmcnt(0)
	v_add_u32_e32 v209, s1, v5
	v_readlane_b32 s1, v255, 8
	s_barrier
	s_nop 0
	v_add_u32_e32 v210, s1, v5
	v_readlane_b32 s1, v255, 9
	s_nop 1
	v_add_u32_e32 v211, s1, v5
	v_readlane_b32 s1, v255, 10
	s_nop 1
	v_add_u32_e32 v212, s1, v5
	s_add_i32 s1, 0, 0x8000
	v_add_u32_e32 v213, s1, v5
	v_readlane_b32 s1, v255, 11
	s_nop 1
	v_add_u32_e32 v214, s1, v5
	v_readlane_b32 s1, v255, 12
	s_nop 1
	v_add_u32_e32 v215, s1, v5
	v_readlane_b32 s1, v255, 13
	s_nop 1
	v_add_u32_e32 v217, s1, v5
	v_readlane_b32 s1, v254, 50
	s_nop 1
	v_add_u32_e32 v218, s1, v5
	v_readlane_b32 s1, v255, 14
	s_nop 1
	v_add_u32_e32 v219, s1, v5
	v_readlane_b32 s1, v255, 15
	s_nop 1
	v_add_u32_e32 v220, s1, v5
	v_readlane_b32 s1, v255, 16
	s_nop 1
	v_add_u32_e32 v221, s1, v5
	v_readlane_b32 s1, v255, 17
	s_nop 1
	v_add_u32_e32 v222, s1, v5
	v_readlane_b32 s1, v255, 18
	s_nop 1
	v_add_u32_e32 v223, s1, v5
	v_readlane_b32 s1, v255, 19
	s_nop 1
	v_add_u32_e32 v224, s1, v5
	v_readlane_b32 s1, v255, 20
	s_nop 1
	v_add_u32_e32 v225, s1, v5
	v_readlane_b32 s1, v255, 21
	s_nop 1
	v_add_u32_e32 v226, s1, v5
	v_readlane_b32 s1, v255, 22
	s_nop 1
	v_add_u32_e32 v227, s1, v5
	v_readlane_b32 s1, v255, 23
	s_nop 1
	v_add_u32_e32 v228, s1, v5
	v_readlane_b32 s1, v255, 24
	s_nop 1
	v_add_u32_e32 v229, s1, v5
	s_add_i32 s1, 0, 0xa000
	v_add_u32_e32 v230, s1, v5
	v_readlane_b32 s1, v255, 25
	s_nop 1
	v_add_u32_e32 v231, s1, v5
	v_readlane_b32 s1, v255, 26
	s_nop 1
	v_add_u32_e32 v232, s1, v5
	v_readlane_b32 s1, v255, 27
	s_nop 1
	v_add_u32_e32 v233, s1, v5
	s_cmp_eq_u64 s[40:41], 0
	s_cbranch_scc0 .Lmla_prio_in
	s_setprio 1
.Lmla_prio_in:
	s_branch .LBB0_765
.LBB0_764:
	s_ashr_i32 s1, s26, 31
	s_lshl_b32 s0, s25, 8
	v_mov_b32_e32 v38, v169
	s_add_u32 s0, s0, s26
	s_nop 0
	v_permlane32_swap_b32_e32 v169, v38
	s_addc_u32 s1, 0, s1
	v_add_f32_e32 v38, v169, v38
	v_lshl_add_u64 v[36:37], s[0:1], 0, v[16:17]
	v_div_scale_f32 v39, s[0:1], v38, v38, 1.0
	v_rcp_f32_e32 v40, v39
	v_lshlrev_b64 v[36:37], 11, v[36:37]
	v_lshl_add_u64 v[36:37], s[36:37], 0, v[36:37]
	s_lshl_b32 s10, s28, 7
	v_fma_f32 v41, -v39, v40, 1.0
	v_fmac_f32_e32 v40, v41, v40
	v_div_scale_f32 v41, vcc, 1.0, v38, 1.0
	v_mul_f32_e32 v42, v41, v40
	v_fma_f32 v43, -v39, v42, v41
	v_fmac_f32_e32 v42, v43, v40
	v_fma_f32 v39, -v39, v42, v41
	v_div_fmas_f32 v39, v39, v40, v42
	v_div_fixup_f32 v38, v39, v38, 1.0
	v_mul_f32_e32 v0, v0, v38
	v_mul_f32_e32 v1, v1, v38
	v_cvt_pk_bf16_f32 v0, v0, v1
	v_mul_f32_e32 v1, v2, v38
	v_mul_f32_e32 v2, v3, v38
	v_lshl_add_u64 v[36:37], v[36:37], 0, s[10:11]
	v_mov_b32_e32 v169, v19
	v_cvt_pk_bf16_f32 v1, v1, v2
	v_mul_f32_e32 v2, v20, v38
	v_mul_f32_e32 v3, v21, v38
	v_lshl_add_u64 v[36:37], v[36:37], 0, v[168:169]
	v_cvt_pk_bf16_f32 v2, v2, v3
	v_mul_f32_e32 v3, v22, v38
	v_mul_f32_e32 v20, v23, v38
	v_cvt_pk_bf16_f32 v3, v3, v20
	global_store_dwordx2 v[36:37], v[0:1], off
	global_store_dwordx2 v[36:37], v[2:3], off offset:64
	v_mul_f32_e32 v0, v4, v38
	v_mul_f32_e32 v1, v5, v38
	v_cvt_pk_bf16_f32 v0, v0, v1
	v_mul_f32_e32 v1, v6, v38
	v_mul_f32_e32 v2, v7, v38
	v_cvt_pk_bf16_f32 v1, v1, v2
	v_mul_f32_e32 v2, v24, v38
	v_mul_f32_e32 v3, v25, v38
	v_cvt_pk_bf16_f32 v2, v2, v3
	v_mul_f32_e32 v3, v26, v38
	v_mul_f32_e32 v4, v27, v38
	v_cvt_pk_bf16_f32 v3, v3, v4
	global_store_dwordx2 v[36:37], v[0:1], off offset:16
	global_store_dwordx2 v[36:37], v[2:3], off offset:80
	v_mul_f32_e32 v0, v8, v38
	v_mul_f32_e32 v1, v9, v38
	v_cvt_pk_bf16_f32 v0, v0, v1
	v_mul_f32_e32 v1, v10, v38
	v_mul_f32_e32 v2, v11, v38
	v_cvt_pk_bf16_f32 v1, v1, v2
	v_mul_f32_e32 v2, v28, v38
	v_mul_f32_e32 v3, v29, v38
	v_cvt_pk_bf16_f32 v2, v2, v3
	v_mul_f32_e32 v3, v30, v38
	v_mul_f32_e32 v4, v31, v38
	v_cvt_pk_bf16_f32 v3, v3, v4
	global_store_dwordx2 v[36:37], v[0:1], off offset:32
	global_store_dwordx2 v[36:37], v[2:3], off offset:96
	v_mul_f32_e32 v0, v12, v38
	v_mul_f32_e32 v1, v13, v38
	v_cvt_pk_bf16_f32 v0, v0, v1
	v_mul_f32_e32 v1, v14, v38
	v_mul_f32_e32 v2, v15, v38
	v_cvt_pk_bf16_f32 v1, v1, v2
	v_mul_f32_e32 v2, v32, v38
	v_mul_f32_e32 v3, v33, v38
	v_readlane_b32 s38, v254, 58
	v_cvt_pk_bf16_f32 v2, v2, v3
	v_mul_f32_e32 v3, v34, v38
	s_andn2_b64 vcc, exec, s[34:35]
	s_mov_b32 s0, s21
	v_readlane_b32 s39, v254, 59
	s_mov_b32 s28, 0xf800000
	s_mov_b32 s52, 0x3fb504f3
	v_mul_f32_e32 v4, v35, v38
	v_cvt_pk_bf16_f32 v3, v3, v4
	global_store_dwordx2 v[36:37], v[0:1], off offset:48
	global_store_dwordx2 v[36:37], v[2:3], off offset:112
	s_cbranch_vccz .LBB0_805

; __device__ __forceinline__ void attn_mla_phase(LAS unsigned char* lds, const bf16_t* QB, const bf16_t* KV, const bf16_t* KRR, bf16_t* O, int G, int bx) {
;     ...
;         if (!hasn) break;
;         li = lin;
;     }
;     ...
; }
.LBB0_805:
	s_setprio 0
	v_readlane_b32 s26, v255, 31
	s_mov_b64 s[30:31], s[70:71]
